# in-projection to mixer transition without drain/barrier/atomic round trip: barrier A tested + invalidate issued at the last tile's epilogue entry, barrier B posted inside LRU pass A's prologue, leader
# speedup vs baseline: 1.0033x; 1.0033x over previous
.Lsb_a1_skip:
	s_cmp_eq_u32 s8, 4
	s_cbranch_scc0 .Lsb_h4_skip
	s_and_saveexec_b64 s[100:101], s[56:57]
	s_cbranch_execz .Lsb_h4_x
	v_readlane_b32 s98, v242, 47
	s_nop 3
	s_cmp_eq_u32 s98, 0
	s_cselect_b32 s98, 0, 8
	s_add_u32 s98, s98, 0x16370d00
	s_add_u32 s98, s68, s98
	s_addc_u32 s99, s69, 0
	v_mov_b32_e32 v245, 0
	global_load_dword v245, v245, s[98:99] sc1

.Lsb_h4_skip:
	s_cmp_eq_u32 s8, 5
	s_cbranch_scc0 .Lsb_h5_skip
	s_and_saveexec_b64 s[100:101], s[56:57]
	s_cbranch_execz .Lsb_h5_x
	v_readlane_b32 s98, v242, 47
	s_nop 3
	s_cmp_eq_u32 s98, 0
	s_cselect_b32 s98, 0, 8
	s_add_u32 s98, s98, 0x16370d00
	s_add_u32 s98, s68, s98
	s_addc_u32 s99, s69, 0
	v_mov_b32_e32 v247, 0x20ff4
	ds_read_b32 v247, v247
	s_waitcnt vmcnt(16) lgkmcnt(0)
	v_cmp_lt_u32_e32 vcc, v245, v247
	s_cbranch_vccz .Lsb_h5_g
	v_mov_b32_e32 v245, 0

.Lsb_h5_g:
	buffer_inv sc1
.Lsb_h5_x:
	s_or_b64 exec, exec, s[100:101]
	v_mov_b32_e32 v245, 0xc0135761
.Lsb_h5_skip:
	v_lshl_or_b32 v172, s10, 8, v190
	v_lshl_add_u32 v168, s9, 8, v189
	v_ashrrev_i32_e32 v173, 31, v172
	v_ashrrev_i32_e32 v169, 31, v168
	v_lshl_add_u64 v[60:61], v[172:173], 2, s[46:47]
	v_lshl_add_u64 v[166:167], v[168:169], 2, s[44:45]
	global_load_dwordx4 v[64:67], v[60:61], off offset:16
	global_load_dwordx4 v[68:71], v[60:61], off
	global_load_dwordx4 v[56:59], v[60:61], off offset:528
	s_nop 0
	global_load_dwordx4 v[60:63], v[60:61], off offset:512
	v_lshlrev_b64 v[172:173], 1, v[172:173]
	global_load_dword v200, v[166:167], off
	global_load_dword v201, v[166:167], off offset:64
	global_load_dword v202, v[166:167], off offset:128
	global_load_dword v203, v[166:167], off offset:192
	global_load_dword v204, v[166:167], off offset:512
	global_load_dword v205, v[166:167], off offset:576
	global_load_dword v206, v[166:167], off offset:640
	global_load_dword v207, v[166:167], off offset:704
	s_waitcnt vmcnt(0)
	v_fmamk_f32 v169, v200, 0x3a000000, v176
	v_readlane_b32 s10, v244, 4
	v_readlane_b32 s11, v244, 5
	v_rsq_f32_e32 v174, v169
	s_nop 0
	v_mov_b64_e32 v[170:171], s[10:11]
	v_mad_i64_i32 v[192:193], s[10:11], v168, s62, v[170:171]
	v_lshl_add_u64 v[192:193], v[192:193], 0, v[172:173]
	v_pk_fma_f32 v[142:143], v[142:143], v[174:175], v[70:71] op_sel_hi:[1,0,1]
	v_pk_fma_f32 v[140:141], v[140:141], v[174:175], v[68:69] op_sel_hi:[1,0,1]
	v_pk_fma_f32 v[194:195], v[138:139], v[174:175], v[66:67] op_sel_hi:[1,0,1]
	v_pk_fma_f32 v[138:139], v[136:137], v[174:175], v[64:65] op_sel_hi:[1,0,1]
	v_cvt_pk_bf16_f32 v136, v140, v141
	v_cvt_pk_bf16_f32 v137, v142, v143
	v_pk_fma_f32 v[134:135], v[134:135], v[174:175], v[62:63] op_sel_hi:[1,0,1]
	v_cvt_pk_bf16_f32 v138, v138, v139
	v_cvt_pk_bf16_f32 v139, v194, v195
	global_store_dwordx4 v[192:193], v[136:139], off
	v_pk_fma_f32 v[132:133], v[132:133], v[174:175], v[60:61] op_sel_hi:[1,0,1]
	s_nop 0
	v_pk_fma_f32 v[136:137], v[130:131], v[174:175], v[58:59] op_sel_hi:[1,0,1]
	v_pk_fma_f32 v[130:131], v[128:129], v[174:175], v[56:57] op_sel_hi:[1,0,1]
	v_cvt_pk_bf16_f32 v128, v132, v133
	v_cvt_pk_bf16_f32 v129, v134, v135
	s_nop 0
	v_cvt_pk_bf16_f32 v130, v130, v131
	v_cvt_pk_bf16_f32 v131, v136, v137
	global_store_dwordx4 v[192:193], v[128:131], off offset:256
	s_nop 0
	s_nop 0
	v_or_b32_e32 v129, 16, v168
	v_fmamk_f32 v128, v201, 0x3a000000, v176
	v_rsq_f32_e32 v128, v128
	v_mad_i64_i32 v[130:131], s[10:11], v129, s62, v[170:171]
	v_lshl_add_u64 v[130:131], v[130:131], 0, v[172:173]
	v_pk_fma_f32 v[126:127], v[126:127], v[128:129], v[70:71] op_sel_hi:[1,0,1]
	v_pk_fma_f32 v[124:125], v[124:125], v[128:129], v[68:69] op_sel_hi:[1,0,1]
	v_pk_fma_f32 v[132:133], v[122:123], v[128:129], v[66:67] op_sel_hi:[1,0,1]
	v_pk_fma_f32 v[122:123], v[120:121], v[128:129], v[64:65] op_sel_hi:[1,0,1]
	v_cvt_pk_bf16_f32 v120, v124, v125
	v_cvt_pk_bf16_f32 v121, v126, v127
	v_pk_fma_f32 v[118:119], v[118:119], v[128:129], v[62:63] op_sel_hi:[1,0,1]
	v_cvt_pk_bf16_f32 v122, v122, v123
	v_cvt_pk_bf16_f32 v123, v132, v133
	global_store_dwordx4 v[130:131], v[120:123], off
	v_pk_fma_f32 v[116:117], v[116:117], v[128:129], v[60:61] op_sel_hi:[1,0,1]
	s_nop 0
	v_pk_fma_f32 v[120:121], v[114:115], v[128:129], v[58:59] op_sel_hi:[1,0,1]
	v_pk_fma_f32 v[114:115], v[112:113], v[128:129], v[56:57] op_sel_hi:[1,0,1]
	v_cvt_pk_bf16_f32 v112, v116, v117
	v_cvt_pk_bf16_f32 v113, v118, v119
	s_nop 0
	v_cvt_pk_bf16_f32 v114, v114, v115
	v_cvt_pk_bf16_f32 v115, v120, v121
	global_store_dwordx4 v[130:131], v[112:115], off offset:256
	s_nop 0
	s_nop 0
	v_or_b32_e32 v113, 32, v168
	v_fmamk_f32 v112, v202, 0x3a000000, v176
	v_rsq_f32_e32 v112, v112
	v_mad_i64_i32 v[114:115], s[10:11], v113, s62, v[170:171]
	v_lshl_add_u64 v[114:115], v[114:115], 0, v[172:173]
	v_pk_fma_f32 v[110:111], v[110:111], v[112:113], v[70:71] op_sel_hi:[1,0,1]
	v_pk_fma_f32 v[108:109], v[108:109], v[112:113], v[68:69] op_sel_hi:[1,0,1]
	v_pk_fma_f32 v[116:117], v[106:107], v[112:113], v[66:67] op_sel_hi:[1,0,1]
	v_pk_fma_f32 v[106:107], v[104:105], v[112:113], v[64:65] op_sel_hi:[1,0,1]
	v_cvt_pk_bf16_f32 v104, v108, v109
	v_cvt_pk_bf16_f32 v105, v110, v111
	v_pk_fma_f32 v[102:103], v[102:103], v[112:113], v[62:63] op_sel_hi:[1,0,1]
	v_cvt_pk_bf16_f32 v106, v106, v107
	v_cvt_pk_bf16_f32 v107, v116, v117
	global_store_dwordx4 v[114:115], v[104:107], off
	v_pk_fma_f32 v[100:101], v[100:101], v[112:113], v[60:61] op_sel_hi:[1,0,1]
	s_nop 0
	v_pk_fma_f32 v[104:105], v[98:99], v[112:113], v[58:59] op_sel_hi:[1,0,1]
	v_pk_fma_f32 v[98:99], v[96:97], v[112:113], v[56:57] op_sel_hi:[1,0,1]
	v_cvt_pk_bf16_f32 v96, v100, v101
	v_cvt_pk_bf16_f32 v97, v102, v103
	s_nop 0
	v_cvt_pk_bf16_f32 v98, v98, v99
	v_cvt_pk_bf16_f32 v99, v104, v105
	global_store_dwordx4 v[114:115], v[96:99], off offset:256
	s_nop 0
	s_nop 0
	v_or_b32_e32 v97, 48, v168
	v_fmamk_f32 v96, v203, 0x3a000000, v176
	v_rsq_f32_e32 v96, v96
	v_mad_i64_i32 v[98:99], s[10:11], v97, s62, v[170:171]
	v_lshl_add_u64 v[98:99], v[98:99], 0, v[172:173]
	v_pk_fma_f32 v[94:95], v[94:95], v[96:97], v[70:71] op_sel_hi:[1,0,1]
	v_pk_fma_f32 v[92:93], v[92:93], v[96:97], v[68:69] op_sel_hi:[1,0,1]
	v_pk_fma_f32 v[100:101], v[90:91], v[96:97], v[66:67] op_sel_hi:[1,0,1]
	v_pk_fma_f32 v[90:91], v[88:89], v[96:97], v[64:65] op_sel_hi:[1,0,1]
	v_cvt_pk_bf16_f32 v88, v92, v93
	v_cvt_pk_bf16_f32 v89, v94, v95
	v_pk_fma_f32 v[86:87], v[86:87], v[96:97], v[62:63] op_sel_hi:[1,0,1]
	v_cvt_pk_bf16_f32 v90, v90, v91
	v_cvt_pk_bf16_f32 v91, v100, v101
	global_store_dwordx4 v[98:99], v[88:91], off
	v_pk_fma_f32 v[84:85], v[84:85], v[96:97], v[60:61] op_sel_hi:[1,0,1]
	s_nop 0
	v_pk_fma_f32 v[88:89], v[82:83], v[96:97], v[58:59] op_sel_hi:[1,0,1]
	v_pk_fma_f32 v[82:83], v[80:81], v[96:97], v[56:57] op_sel_hi:[1,0,1]
	v_cvt_pk_bf16_f32 v80, v84, v85
	v_cvt_pk_bf16_f32 v81, v86, v87
	s_nop 0
	v_cvt_pk_bf16_f32 v82, v82, v83
	v_cvt_pk_bf16_f32 v83, v88, v89
	global_store_dwordx4 v[98:99], v[80:83], off offset:256
	s_nop 0
	s_nop 0
	v_add_u32_e32 v81, 0x80, v168
	v_fmamk_f32 v80, v204, 0x3a000000, v176
	v_rsq_f32_e32 v80, v80
	v_mad_i64_i32 v[82:83], s[10:11], v81, s62, v[170:171]
	v_lshl_add_u64 v[82:83], v[82:83], 0, v[172:173]
	v_pk_fma_f32 v[78:79], v[78:79], v[80:81], v[70:71] op_sel_hi:[1,0,1]
	v_pk_fma_f32 v[76:77], v[76:77], v[80:81], v[68:69] op_sel_hi:[1,0,1]
	v_pk_fma_f32 v[84:85], v[74:75], v[80:81], v[66:67] op_sel_hi:[1,0,1]
	v_pk_fma_f32 v[74:75], v[72:73], v[80:81], v[64:65] op_sel_hi:[1,0,1]
	v_cvt_pk_bf16_f32 v72, v76, v77
	v_cvt_pk_bf16_f32 v73, v78, v79
	v_pk_fma_f32 v[54:55], v[54:55], v[80:81], v[62:63] op_sel_hi:[1,0,1]
	v_cvt_pk_bf16_f32 v74, v74, v75
	v_cvt_pk_bf16_f32 v75, v84, v85
	global_store_dwordx4 v[82:83], v[72:75], off
	v_pk_fma_f32 v[52:53], v[52:53], v[80:81], v[60:61] op_sel_hi:[1,0,1]
	s_nop 0
	v_pk_fma_f32 v[72:73], v[50:51], v[80:81], v[58:59] op_sel_hi:[1,0,1]
	v_pk_fma_f32 v[50:51], v[48:49], v[80:81], v[56:57] op_sel_hi:[1,0,1]
	v_cvt_pk_bf16_f32 v48, v52, v53
	v_cvt_pk_bf16_f32 v49, v54, v55
	s_nop 0
	v_cvt_pk_bf16_f32 v50, v50, v51
	v_cvt_pk_bf16_f32 v51, v72, v73
	global_store_dwordx4 v[82:83], v[48:51], off offset:256
	s_nop 0
	s_nop 0
	v_add_u32_e32 v49, 0x90, v168
	v_fmamk_f32 v48, v205, 0x3a000000, v176
	v_rsq_f32_e32 v48, v48
	v_mad_i64_i32 v[50:51], s[10:11], v49, s62, v[170:171]
	v_lshl_add_u64 v[50:51], v[50:51], 0, v[172:173]
	v_pk_fma_f32 v[46:47], v[46:47], v[48:49], v[70:71] op_sel_hi:[1,0,1]
	v_pk_fma_f32 v[44:45], v[44:45], v[48:49], v[68:69] op_sel_hi:[1,0,1]
	v_pk_fma_f32 v[52:53], v[42:43], v[48:49], v[66:67] op_sel_hi:[1,0,1]
	v_pk_fma_f32 v[42:43], v[40:41], v[48:49], v[64:65] op_sel_hi:[1,0,1]
	v_cvt_pk_bf16_f32 v40, v44, v45
	v_cvt_pk_bf16_f32 v41, v46, v47
	v_pk_fma_f32 v[38:39], v[38:39], v[48:49], v[62:63] op_sel_hi:[1,0,1]
	v_cvt_pk_bf16_f32 v42, v42, v43
	v_cvt_pk_bf16_f32 v43, v52, v53
	global_store_dwordx4 v[50:51], v[40:43], off
	v_pk_fma_f32 v[36:37], v[36:37], v[48:49], v[60:61] op_sel_hi:[1,0,1]
	s_nop 0
	v_pk_fma_f32 v[40:41], v[34:35], v[48:49], v[58:59] op_sel_hi:[1,0,1]
	v_pk_fma_f32 v[34:35], v[32:33], v[48:49], v[56:57] op_sel_hi:[1,0,1]
	v_cvt_pk_bf16_f32 v32, v36, v37
	v_cvt_pk_bf16_f32 v33, v38, v39
	s_nop 0
	v_cvt_pk_bf16_f32 v34, v34, v35
	v_cvt_pk_bf16_f32 v35, v40, v41
	global_store_dwordx4 v[50:51], v[32:35], off offset:256
	s_nop 0
	s_nop 0
	v_add_u32_e32 v33, 0xa0, v168
	v_fmamk_f32 v32, v206, 0x3a000000, v176
	v_rsq_f32_e32 v32, v32
	v_mad_i64_i32 v[34:35], s[10:11], v33, s62, v[170:171]
	v_lshl_add_u64 v[34:35], v[34:35], 0, v[172:173]
	v_pk_fma_f32 v[30:31], v[30:31], v[32:33], v[70:71] op_sel_hi:[1,0,1]
	v_pk_fma_f32 v[28:29], v[28:29], v[32:33], v[68:69] op_sel_hi:[1,0,1]
	v_pk_fma_f32 v[36:37], v[26:27], v[32:33], v[66:67] op_sel_hi:[1,0,1]
	v_pk_fma_f32 v[26:27], v[24:25], v[32:33], v[64:65] op_sel_hi:[1,0,1]
	v_cvt_pk_bf16_f32 v24, v28, v29
	v_cvt_pk_bf16_f32 v25, v30, v31
	v_pk_fma_f32 v[22:23], v[22:23], v[32:33], v[62:63] op_sel_hi:[1,0,1]
	v_cvt_pk_bf16_f32 v26, v26, v27
	v_cvt_pk_bf16_f32 v27, v36, v37
	global_store_dwordx4 v[34:35], v[24:27], off
	v_pk_fma_f32 v[20:21], v[20:21], v[32:33], v[60:61] op_sel_hi:[1,0,1]
	s_nop 0
	v_pk_fma_f32 v[24:25], v[18:19], v[32:33], v[58:59] op_sel_hi:[1,0,1]
	v_pk_fma_f32 v[18:19], v[16:17], v[32:33], v[56:57] op_sel_hi:[1,0,1]
	v_cvt_pk_bf16_f32 v16, v20, v21
	v_cvt_pk_bf16_f32 v17, v22, v23
	s_nop 0
	v_cvt_pk_bf16_f32 v18, v18, v19
	v_cvt_pk_bf16_f32 v19, v24, v25
	global_store_dwordx4 v[34:35], v[16:19], off offset:256
	s_nop 0
	s_nop 0
	v_add_u32_e32 v17, 0xb0, v168
	v_fmamk_f32 v16, v207, 0x3a000000, v176
	s_mov_b64 s[42:43], -1
	v_rsq_f32_e32 v16, v16
	v_mad_i64_i32 v[18:19], s[10:11], v17, s62, v[170:171]
	v_lshl_add_u64 v[18:19], v[18:19], 0, v[172:173]
	v_pk_fma_f32 v[14:15], v[14:15], v[16:17], v[70:71] op_sel_hi:[1,0,1]
	v_pk_fma_f32 v[12:13], v[12:13], v[16:17], v[68:69] op_sel_hi:[1,0,1]
	v_pk_fma_f32 v[20:21], v[10:11], v[16:17], v[66:67] op_sel_hi:[1,0,1]
	v_pk_fma_f32 v[10:11], v[8:9], v[16:17], v[64:65] op_sel_hi:[1,0,1]
	v_cvt_pk_bf16_f32 v8, v12, v13
	v_cvt_pk_bf16_f32 v9, v14, v15
	s_andn2_b64 vcc, exec, s[40:41]
	v_cvt_pk_bf16_f32 v10, v10, v11
	v_cvt_pk_bf16_f32 v11, v20, v21
	global_store_dwordx4 v[18:19], v[8:11], off
	v_pk_fma_f32 v[6:7], v[6:7], v[16:17], v[62:63] op_sel_hi:[1,0,1]
	v_pk_fma_f32 v[4:5], v[4:5], v[16:17], v[60:61] op_sel_hi:[1,0,1]
	v_pk_fma_f32 v[8:9], v[2:3], v[16:17], v[58:59] op_sel_hi:[1,0,1]
	v_pk_fma_f32 v[2:3], v[0:1], v[16:17], v[56:57] op_sel_hi:[1,0,1]
	v_cvt_pk_bf16_f32 v0, v4, v5
	v_cvt_pk_bf16_f32 v1, v6, v7
	s_nop 0
	v_cvt_pk_bf16_f32 v2, v2, v3
	v_cvt_pk_bf16_f32 v3, v8, v9
	global_store_dwordx4 v[18:19], v[0:3], off offset:256
	s_cbranch_vccnz .LBB0_241
	s_andn2_b64 vcc, exec, s[0:1]
	s_cbranch_vccnz .LBB0_240
	s_barrier
	s_branch .LBB0_240

.LBB0_263:
	s_mul_i32 s0, s96, 5
	s_add_i32 s4, s0, 3
	s_waitcnt vmcnt(16)
	s_branch .LBB0_329
	s_cmp_ge_i32 s4, s71
	s_cbranch_scc1 .LBB0_329
	v_readlane_b32 s0, v244, 18
	v_readlane_b32 s1, v244, 19
	s_andn2_b64 vcc, exec, s[0:1]
	s_cbranch_vccnz .LBB0_276
	s_barrier
	s_mov_b64 s[0:1], exec
	v_readlane_b32 s6, v242, 6
	v_readlane_b32 s7, v242, 7
	s_and_b64 s[6:7], s[0:1], s[6:7]
	s_mov_b64 exec, s[6:7]
	s_cbranch_execz .LBB0_275
	v_readlane_b32 s6, v244, 0
	v_readlane_b32 s7, v244, 1
	buffer_wbl2 sc1
	s_waitcnt vmcnt(0)
	s_load_dwordx2 s[40:41], s[6:7], 0x58
	s_mov_b64 s[42:43], exec
	v_mbcnt_lo_u32_b32 v1, s42, 0
	v_mbcnt_hi_u32_b32 v1, s43, v1
	v_cmp_eq_u32_e32 vcc, 0, v1
	s_waitcnt lgkmcnt(0)
	global_load_dword v0, v145, s[40:41] offset:40
	s_and_saveexec_b64 s[44:45], vcc
	s_cbranch_execz .LBB0_268
	s_bcnt1_i32_b64 s5, s[42:43]
	v_mov_b32_e32 v2, s5
	global_atomic_add v2, v145, v2, s[40:41] offset:32 sc0

.LBB0_343:
	s_or_b64 exec, exec, s[42:43]
	v_mul_f32_e32 v8, 0xbfb8aa3b, v8
	v_exp_f32_e32 v10, v8
	s_mov_b32 s5, 0x3f2aaaab
	s_mov_b32 s6, 0x3f317218
	s_mov_b32 s7, 0x7f800000
	v_add_f32_e32 v11, 1.0, v10
	v_frexp_mant_f32_e32 v13, v11
	v_cvt_f64_f32_e32 v[8:9], v11
	v_add_f32_e32 v12, -1.0, v11
	v_frexp_exp_i32_f64_e32 v8, v[8:9]
	v_cmp_gt_f32_e32 vcc, s5, v13
	v_sub_f32_e32 v14, v12, v11
	v_sub_f32_e32 v12, v10, v12
	v_subbrev_co_u32_e32 v8, vcc, 0, v8, vcc
	v_add_f32_e32 v14, 1.0, v14
	v_sub_u32_e32 v9, 0, v8
	v_add_f32_e32 v12, v12, v14
	v_ldexp_f32 v11, v11, v9
	v_ldexp_f32 v9, v12, v9
	v_add_f32_e32 v12, -1.0, v11
	v_add_f32_e32 v15, 1.0, v11
	v_add_f32_e32 v13, 1.0, v12
	v_add_f32_e32 v16, -1.0, v15
	v_sub_f32_e32 v13, v11, v13
	v_sub_f32_e32 v11, v11, v16
	v_add_f32_e32 v13, v9, v13
	v_add_f32_e32 v9, v9, v11
	v_add_f32_e32 v11, v15, v9
	v_rcp_f32_e32 v16, v11
	v_add_f32_e32 v14, v12, v13
	v_sub_f32_e32 v12, v14, v12
	v_sub_f32_e32 v12, v13, v12
	v_sub_f32_e32 v13, v11, v15
	v_sub_f32_e32 v9, v9, v13
	v_mul_f32_e32 v13, v14, v16
	v_mul_f32_e32 v15, v11, v13
	v_fma_f32 v17, v13, v11, -v15
	v_fmac_f32_e32 v17, v13, v9
	v_add_f32_e32 v18, v15, v17
	v_sub_f32_e32 v19, v14, v18
	v_sub_f32_e32 v14, v14, v19
	v_sub_f32_e32 v15, v18, v15
	v_sub_f32_e32 v14, v14, v18
	v_add_f32_e32 v12, v12, v14
	v_sub_f32_e32 v14, v15, v17
	v_add_f32_e32 v12, v14, v12
	v_add_f32_e32 v14, v19, v12
	v_mul_f32_e32 v15, v16, v14
	v_mul_f32_e32 v17, v11, v15
	v_fma_f32 v11, v15, v11, -v17
	v_fmac_f32_e32 v11, v15, v9
	v_sub_f32_e32 v9, v19, v14
	v_add_f32_e32 v9, v12, v9
	v_add_f32_e32 v12, v17, v11
	v_sub_f32_e32 v18, v14, v12
	v_sub_f32_e32 v14, v14, v18
	v_sub_f32_e32 v17, v12, v17
	v_sub_f32_e32 v12, v14, v12
	v_add_f32_e32 v9, v9, v12
	v_sub_f32_e32 v11, v17, v11
	v_cvt_f32_i32_e32 v8, v8
	v_add_f32_e32 v9, v11, v9
	v_add_f32_e32 v11, v13, v15
	v_add_f32_e32 v9, v18, v9
	v_sub_f32_e32 v12, v11, v13
	v_mul_f32_e32 v9, v16, v9
	v_sub_f32_e32 v12, v15, v12
	v_add_f32_e32 v9, v12, v9
	v_mul_f32_e32 v15, 0x3f317218, v8
	v_add_f32_e32 v12, v11, v9
	v_fma_f32 v16, v8, s6, -v15
	v_mul_f32_e32 v13, v12, v12
	v_fmac_f32_e32 v16, 0xb102e308, v8
	v_sub_f32_e32 v8, v12, v11
	v_fmamk_f32 v14, v13, 0x3e9b6dac, v179
	v_sub_f32_e32 v8, v9, v8
	v_add_f32_e32 v9, v15, v16
	v_fmaak_f32 v14, v13, v14, 0x3f2aaada
	v_sub_f32_e32 v11, v9, v15
	v_ldexp_f32 v15, v12, 1
	v_mul_f32_e32 v12, v12, v13
	v_mul_f32_e32 v12, v12, v14
	v_add_f32_e32 v13, v15, v12
	v_sub_f32_e32 v14, v13, v15
	v_ldexp_f32 v8, v8, 1
	v_sub_f32_e32 v12, v12, v14
	v_add_f32_e32 v8, v8, v12
	v_add_f32_e32 v12, v13, v8
	v_sub_f32_e32 v13, v12, v13
	v_sub_f32_e32 v8, v8, v13
	v_add_f32_e32 v13, v9, v12
	v_sub_f32_e32 v14, v13, v9
	v_sub_f32_e32 v15, v13, v14
	v_sub_f32_e32 v11, v16, v11
	v_sub_f32_e32 v9, v9, v15
	v_sub_f32_e32 v12, v12, v14
	v_add_f32_e32 v9, v12, v9
	v_add_f32_e32 v12, v11, v8
	v_sub_f32_e32 v14, v12, v11
	v_sub_f32_e32 v15, v12, v14
	v_sub_f32_e32 v11, v11, v15
	v_sub_f32_e32 v8, v8, v14
	v_add_f32_e32 v9, v12, v9
	v_add_f32_e32 v8, v8, v11
	v_add_f32_e32 v11, v13, v9
	v_sub_f32_e32 v12, v11, v13
	v_sub_f32_e32 v9, v9, v12
	v_add_f32_e32 v8, v8, v9
	v_mul_f32_e32 v7, 0xbfb8aa3b, v7
	v_add_f32_e32 v8, v11, v8
	v_cmp_neq_f32_e32 vcc, s7, v10
	v_exp_f32_e32 v7, v7
	s_mov_b32 s8, 0x33800000
	v_cndmask_b32_e32 v8, v182, v8, vcc
	v_cmp_ngt_f32_e32 vcc, -1.0, v10
	v_lshl_add_u64 v[64:65], s[44:45], 0, v[144:145]
	v_cmp_gt_u32_e64 s[42:43], 32, v5
	v_cndmask_b32_e32 v8, v183, v8, vcc
	v_cmp_neq_f32_e32 vcc, -1.0, v10
	s_mov_b32 s4, 0
	v_add_u32_e32 v100, -2, v6
	v_cndmask_b32_e32 v8, v184, v8, vcc
	v_cmp_lt_f32_e64 vcc, |v10|, s8
	s_waitcnt lgkmcnt(0)
	s_barrier
	s_and_saveexec_b64 s[100:101], s[56:57]
	s_cbranch_execz .Lsb_pb_x
	v_readlane_b32 s98, v242, 47
	s_nop 3
	s_cmp_eq_u32 s98, 0
	s_cselect_b32 s99, 0, 128
	s_getreg_b32 s98, hwreg(HW_REG_XCC_ID, 0, 4)
	s_lshl_b32 s98, s98, 2
	s_add_u32 s98, s98, s99
	s_add_u32 s98, s98, 0x16370e40
	s_add_u32 s98, s68, s98
	s_addc_u32 s99, s69, 0
	v_mov_b32_e32 v246, 0
	v_mov_b32_e32 v247, 1
	global_atomic_add v247, v246, v247, s[98:99] sc0
.Lsb_pb_x:
	s_or_b64 exec, exec, s[100:101]
	s_mov_b32 s99, 1
	v_cndmask_b32_e32 v8, v8, v10, vcc
	v_add_f32_e32 v10, 1.0, v7
	v_mul_f32_e32 v92, 0xc1000000, v8
	v_add_f32_e32 v8, -1.0, v10
	v_sub_f32_e32 v9, v8, v10
	v_add_f32_e32 v9, 1.0, v9
	v_sub_f32_e32 v8, v7, v8
	v_add_f32_e32 v11, v8, v9
	v_frexp_mant_f32_e32 v12, v10
	v_cvt_f64_f32_e32 v[8:9], v10
	v_frexp_exp_i32_f64_e32 v8, v[8:9]
	v_cmp_gt_f32_e32 vcc, s5, v12
	v_readlane_b32 s5, v242, 3
	s_nop 0
	v_subbrev_co_u32_e32 v8, vcc, 0, v8, vcc
	v_sub_u32_e32 v9, 0, v8
	v_ldexp_f32 v10, v10, v9
	v_ldexp_f32 v9, v11, v9
	v_add_f32_e32 v11, -1.0, v10
	v_add_f32_e32 v14, 1.0, v10
	v_add_f32_e32 v12, 1.0, v11
	v_add_f32_e32 v15, -1.0, v14
	v_sub_f32_e32 v12, v10, v12
	v_sub_f32_e32 v10, v10, v15
	v_add_f32_e32 v12, v9, v12
	v_add_f32_e32 v9, v9, v10
	v_add_f32_e32 v10, v14, v9
	v_rcp_f32_e32 v15, v10
	v_add_f32_e32 v13, v11, v12
	v_sub_f32_e32 v11, v13, v11
	v_sub_f32_e32 v11, v12, v11
	v_sub_f32_e32 v12, v10, v14
	v_sub_f32_e32 v9, v9, v12
	v_mul_f32_e32 v12, v13, v15
	v_mul_f32_e32 v14, v10, v12
	v_fma_f32 v16, v12, v10, -v14
	v_fmac_f32_e32 v16, v12, v9
	v_add_f32_e32 v17, v14, v16
	v_sub_f32_e32 v18, v13, v17
	v_sub_f32_e32 v13, v13, v18
	v_sub_f32_e32 v14, v17, v14
	v_sub_f32_e32 v13, v13, v17
	v_add_f32_e32 v11, v11, v13
	v_sub_f32_e32 v13, v14, v16
	v_add_f32_e32 v11, v13, v11
	v_add_f32_e32 v13, v18, v11
	v_mul_f32_e32 v14, v15, v13
	v_mul_f32_e32 v16, v10, v14
	v_fma_f32 v10, v14, v10, -v16
	v_fmac_f32_e32 v10, v14, v9
	v_sub_f32_e32 v9, v18, v13
	v_add_f32_e32 v9, v11, v9
	v_add_f32_e32 v11, v16, v10
	v_sub_f32_e32 v17, v13, v11
	v_sub_f32_e32 v13, v13, v17
	v_sub_f32_e32 v16, v11, v16
	v_sub_f32_e32 v11, v13, v11
	v_add_f32_e32 v9, v9, v11
	v_sub_f32_e32 v10, v16, v10
	v_cvt_f32_i32_e32 v8, v8
	v_add_f32_e32 v9, v10, v9
	v_add_f32_e32 v10, v12, v14
	v_add_f32_e32 v9, v17, v9
	v_sub_f32_e32 v11, v10, v12
	v_mul_f32_e32 v9, v15, v9
	v_sub_f32_e32 v11, v14, v11
	v_add_f32_e32 v9, v11, v9
	v_mul_f32_e32 v14, 0x3f317218, v8
	v_add_f32_e32 v11, v10, v9
	v_fma_f32 v15, v8, s6, -v14
	v_mul_f32_e32 v12, v11, v11
	v_fmac_f32_e32 v15, 0xb102e308, v8
	v_sub_f32_e32 v8, v11, v10
	v_fmamk_f32 v13, v12, 0x3e9b6dac, v179
	v_sub_f32_e32 v8, v9, v8
	v_add_f32_e32 v9, v14, v15
	v_fmaak_f32 v13, v12, v13, 0x3f2aaada
	v_sub_f32_e32 v10, v9, v14
	v_ldexp_f32 v14, v11, 1
	v_mul_f32_e32 v11, v11, v12
	v_mul_f32_e32 v11, v11, v13
	v_add_f32_e32 v12, v14, v11
	v_sub_f32_e32 v13, v12, v14
	v_ldexp_f32 v8, v8, 1
	v_sub_f32_e32 v11, v11, v13
	v_add_f32_e32 v8, v8, v11
	v_add_f32_e32 v11, v12, v8
	v_sub_f32_e32 v12, v11, v12
	v_sub_f32_e32 v8, v8, v12
	v_add_f32_e32 v12, v9, v11
	v_sub_f32_e32 v13, v12, v9
	v_sub_f32_e32 v14, v12, v13
	v_sub_f32_e32 v10, v15, v10
	v_sub_f32_e32 v9, v9, v14
	v_sub_f32_e32 v11, v11, v13
	v_add_f32_e32 v9, v11, v9
	v_add_f32_e32 v11, v10, v8
	v_sub_f32_e32 v13, v11, v10
	v_sub_f32_e32 v14, v11, v13
	v_sub_f32_e32 v10, v10, v14
	v_sub_f32_e32 v8, v8, v13
	v_add_f32_e32 v9, v11, v9
	v_add_f32_e32 v8, v8, v10
	v_add_f32_e32 v10, v12, v9
	v_sub_f32_e32 v11, v10, v12
	v_sub_f32_e32 v9, v9, v11
	v_add_f32_e32 v8, v8, v9
	v_add_f32_e32 v8, v10, v8
	v_lshlrev_b32_e32 v10, 2, v0
	v_and_b32_e32 v10, 60, v10
	v_lshlrev_b32_e32 v11, 2, v10
	v_cmp_neq_f32_e32 vcc, s7, v7
	v_add_u32_e32 v94, 0, v11
	v_lshlrev_b32_e32 v10, 1, v10
	v_readlane_b32 s7, v242, 4
	v_sub_u32_e32 v95, v94, v10
	s_movk_i32 s6, 0x90
	v_add_u32_e32 v96, s7, v10
	v_and_b32_e32 v10, 0xffffffe0, v88
	v_or_b32_e32 v4, v10, v4
	v_cndmask_b32_e32 v8, v182, v8, vcc
	v_cmp_ngt_f32_e32 vcc, -1.0, v7
	v_mul_lo_u32 v4, v4, s6
	v_lshlrev_b32_e32 v14, 12, v1
	v_and_b32_e32 v1, 0x1fffff80, v0
	v_cndmask_b32_e32 v8, v183, v8, vcc
	v_cmp_neq_f32_e32 vcc, -1.0, v7
	v_lshlrev_b32_e32 v9, 3, v3
	v_add_u32_e32 v4, s7, v4
	v_lshlrev_b32_e32 v1, 3, v1
	v_readlane_b32 s7, v242, 2
	v_cndmask_b32_e32 v8, v184, v8, vcc
	v_cmp_lt_f32_e64 vcc, |v7|, s8
	v_add3_u32 v97, s7, v9, v1
	v_and_b32_e32 v1, 0x1fffffc0, v0
	v_cndmask_b32_e32 v7, v8, v7, vcc
	v_lshlrev_b32_e32 v8, 3, v5
	v_add_u32_e32 v11, s5, v11
	v_lshl_add_u32 v3, v3, 2, s5
	s_movk_i32 s5, 0x80
	v_lshlrev_b32_e32 v1, 3, v1
	v_mul_f32_e32 v93, 0xc1000000, v7
	v_lshrrev_b32_e32 v7, 5, v5
	v_and_b32_e32 v12, -4, v88
	v_lshl_add_u32 v15, v5, 4, 0
	v_cmp_gt_i32_e64 s[44:45], s5, v0
	v_add3_u32 v5, s7, v8, v1
	v_or_b32_e32 v1, 3, v88
	s_movk_i32 s5, 0x110
	v_mul_lo_u32 v98, v12, s6
	v_mul_lo_u32 v99, v1, s6
	v_mul_lo_u32 v9, v12, s5
	v_mul_lo_u32 v12, v1, s5
	v_lshl_or_b32 v1, v7, 2, v10
	v_lshlrev_b32_e32 v13, 4, v7
	v_mul_lo_u32 v7, v1, s5
	v_readlane_b32 s5, v243, 55
	s_add_u32 s0, s0, s5
	v_readlane_b32 s5, v243, 56
	s_addc_u32 s1, s1, s5
	s_mov_b32 s5, 0x104000
	v_cmp_gt_u32_e32 vcc, 64, v0
	v_mad_i64_i32 v[0:1], s[6:7], v2, s5, 0
	v_or_b32_e32 v0, v0, v8
	v_cndmask_b32_e64 v10, v185, 0, vcc
	v_cndmask_b32_e32 v16, v186, v187, vcc
	v_cndmask_b32_e32 v17, v187, v186, vcc
	v_cndmask_b32_e32 v18, 0, v185, vcc
	v_lshl_add_u64 v[66:67], s[0:1], 0, v[0:1]
	v_readlane_b32 s0, v243, 57
	v_add_u32_e32 v101, v11, v9
	v_add_u32_e32 v102, v11, v12
	v_add_u32_e32 v103, v4, v13
	v_add_u32_e32 v104, v3, v7
	v_add_u32_e32 v105, v5, v10
	v_add_u32_e32 v106, v5, v16
	v_add_u32_e32 v107, v5, v17
	v_add_u32_e32 v108, v5, v18
	v_add_u32_e32 v109, v15, v14
	v_readlane_b32 s5, v243, 60
	s_mov_b32 s6, s0
	v_readlane_b32 s1, v243, 58
	v_mul_f32_e32 v84, 0xbfb8aa3b, v84
	v_mul_f32_e32 v85, 0xbfb8aa3b, v85
	v_mul_f32_e32 v86, 0xbfb8aa3b, v86
	v_mul_f32_e32 v87, 0xbfb8aa3b, v87
	v_mul_f32_e32 v92, 0x3fb8aa3b, v92
	v_mul_f32_e32 v93, 0x3fb8aa3b, v93
	s_branch .LBB0_345

.LBB0_355:
	s_or_b64 exec, exec, s[46:47]
	s_andn2_b64 vcc, exec, s[48:49]
	s_cbranch_vccnz .LBB0_359
	s_xor_b32 s7, s4, 1
	s_mulk_i32 s7, 0x4a40
	s_add_i32 s7, s7, 0
	s_waitcnt lgkmcnt(3)
	v_add3_u32 v0, s7, v89, v90
	s_waitcnt vmcnt(0)
	s_cmp_eq_u32 s99, 0
	s_cbranch_scc1 .Lsb_c1_skip
	s_mov_b32 s99, 0
	s_and_saveexec_b64 s[100:101], s[56:57]
	s_cbranch_execz .Lsb_c1_x
	v_mov_b32_e32 v246, 0x20ff0
	ds_read_b32 v246, v246
	s_waitcnt vmcnt(0) lgkmcnt(0)
	v_add_u32_e32 v247, 1, v247
	v_cmp_eq_u32_e32 vcc, v247, v246
	s_cbranch_vccz .Lsb_c1_x
	buffer_wbl2 sc1
	s_waitcnt vmcnt(0)
	v_readlane_b32 s98, v242, 47
	s_nop 3
	s_cmp_eq_u32 s98, 0
	s_cselect_b32 s98, 0, 8
	s_add_u32 s98, s98, 0x16370d04
	s_add_u32 s98, s68, s98
	s_addc_u32 s99, s69, 0
	v_mov_b32_e32 v246, 0
	v_mov_b32_e32 v247, 1
	global_atomic_add v246, v247, s[98:99]
	s_waitcnt vmcnt(0)
.Lsb_c1_x:
	s_or_b64 exec, exec, s[100:101]
	s_mov_b32 s99, 0
.Lsb_c1_skip:
	ds_write_b128 v0, v[36:39] offset:35104
	ds_write_b128 v0, v[32:35] offset:35120
	s_and_saveexec_b64 s[46:47], s[40:41]
	s_cbranch_execz .LBB0_358
	v_add3_u32 v0, s7, v91, v90
	ds_write_b128 v0, v[44:47] offset:34816
	ds_write_b128 v0, v[40:43] offset:34832

.LBB0_361:
	s_waitcnt vmcnt(0)
	s_cmp_eq_u32 s99, 0
	s_cbranch_scc1 .Lsb_c2_skip
	s_mov_b32 s99, 0
	s_and_saveexec_b64 s[100:101], s[56:57]
	s_cbranch_execz .Lsb_c2_x
	v_mov_b32_e32 v246, 0x20ff0
	ds_read_b32 v246, v246
	s_waitcnt vmcnt(0) lgkmcnt(0)
	v_add_u32_e32 v247, 1, v247
	v_cmp_eq_u32_e32 vcc, v247, v246
	s_cbranch_vccz .Lsb_c2_x
	buffer_wbl2 sc1
	s_waitcnt vmcnt(0)
	v_readlane_b32 s98, v242, 47
	s_nop 3
	s_cmp_eq_u32 s98, 0
	s_cselect_b32 s98, 0, 8
	s_add_u32 s98, s98, 0x16370d04
	s_add_u32 s98, s68, s98
	s_addc_u32 s99, s69, 0
	v_mov_b32_e32 v246, 0
	v_mov_b32_e32 v247, 1
	global_atomic_add v246, v247, s[98:99]
	s_waitcnt vmcnt(0)

.Lsb_c2_skip:
	s_barrier
	s_and_saveexec_b64 s[100:101], s[56:57]
	s_and_b32 s98, s2, 15
	s_lshl_b32 s99, s96, 4
	s_add_i32 s98, s98, s99
	s_lshl_b32 s98, s98, 2
	s_add_u32 s98, s98, 0x16370d80
	s_add_u32 s98, s68, s98
	s_addc_u32 s99, s69, 0
	v_mov_b32_e32 v246, 0
	v_mov_b32_e32 v247, 1
	global_atomic_add v246, v247, s[98:99]
	s_or_b64 exec, exec, s[100:101]
	s_and_saveexec_b64 s[100:101], s[56:57]
	s_cbranch_execz .Lsb_wB_x
	v_readlane_b32 s98, v242, 47
	s_nop 3
	s_cmp_eq_u32 s98, 0
	s_cselect_b32 s98, 0, 8
	s_add_u32 s98, s98, 0x16370d04
	s_add_u32 s98, s68, s98
	s_addc_u32 s99, s69, 0
	v_mov_b32_e32 v247, 0x20ff4
	ds_read_b32 v247, v247
	v_mov_b32_e32 v245, 0
	s_waitcnt lgkmcnt(0)
